# MLA leading half stages tile n+1 into LDS 16 instructions into the exp block instead of right after QK (loads get more time; softmax starts sooner)
# speedup vs baseline: 1.0128x; 1.0009x over previous
; #define SBAR() __builtin_amdgcn_sched_barrier(0)
; #define SWRITE(b) do { *(bf16x8*)(V_lds + (b) * SHM_V + vst0) = svs0; *(bf16x8*)(V_lds + (b) * SHM_V + vst1) = svs1; \
;     _Pragma("unroll") for (int i_ = 0; i_ < NKP; ++i_) *(bf16x8*)(K_lds + (b) * KT + klds[i_]) = sks[i_]; } while (0)
; #define SWAIT() asm volatile("s_waitcnt vmcnt(0)" ::: "memory")
; template <int DQK, int NQR>
; DEV void qkt(f32x16& p0, f32x16& p1, const char* Ks, const bf16x8* qr, const char* qlds_, int r32, int hi) {
;     ...
;   for (int d0 = 0; d0 < DQK / 16; ++d0) {
;     const int cb = (d0 * 16 + hi * 8) * 2;
;     bf16x8 b0 = *reinterpret_cast<const bf16x8*>(Ks + r32 * KROW + cb);
;     bf16x8 b1 = *reinterpret_cast<const bf16x8*>(Ks + (32 + r32) * KROW + cb);
;     bf16x8 q;
;     if (d0 < NQR) q = qr[d0 < NQR ? d0 : 0]; else q = *reinterpret_cast<const __attribute__((address_space(3))) bf16x8*>(qlds + (d0 - NQR) * 1024);
;     p0 = __builtin_amdgcn_mfma_f32_32x32x16_bf16(b0, q, p0, 0, 0, 0);
;     p1 = __builtin_amdgcn_mfma_f32_32x32x16_bf16(b1, q, p1, 0, 0, 0);
;     if (NQR < DQK / 16 && (d0 & 3) == 3) SBAR();
; template <int DQK, bool WIN, bool TWO>
; DEV void attn_unit(const bf16_t* Qb, int ldq, const bf16_t* __restrict__ Kh, int ldk, const bf16_t* __restrict__ Vh, int ldv,
;                    bf16_t* Ob, int ldo, int kbeg, int NT, int q0, float sink, const float SCALE, char* lds) {
;     ...
;     if (j + 1 < NT) { SWAIT(); if (bf) SWRITE(0); else SWRITE(1); }
.Lmla_qk_lead:
	s_waitcnt lgkmcnt(4)
	v_mfma_f32_32x32x16_bf16 v[80:95], v[188:191], v[104:107], v[80:95]
	v_mfma_f32_32x32x16_bf16 v[64:79], v[198:201], v[104:107], v[64:79]
	s_waitcnt lgkmcnt(2)
	v_mfma_f32_32x32x16_bf16 v[80:95], v[214:217], v[100:103], v[80:95]
	v_mfma_f32_32x32x16_bf16 v[64:79], v[218:221], v[100:103], v[64:79]
	s_waitcnt lgkmcnt(0)
	v_mfma_f32_32x32x16_bf16 v[80:95], v[222:225], v[96:99], v[80:95]
	v_mfma_f32_32x32x16_bf16 v[64:79], v[242:245], v[96:99], v[64:79]
	s_setprio 0
	s_nop 7
	s_nop 1

; #define SWRITE(b) do { *(bf16x8*)(V_lds + (b) * SHM_V + vst0) = svs0; *(bf16x8*)(V_lds + (b) * SHM_V + vst1) = svs1; \
;     _Pragma("unroll") for (int i_ = 0; i_ < NKP; ++i_) *(bf16x8*)(K_lds + (b) * KT + klds[i_]) = sks[i_]; } while (0)
; #define SWAIT() asm volatile("s_waitcnt vmcnt(0)" ::: "memory")
; DEV void finishSM(f32x16& p0, f32x16& p1, float alpha, float& l_reg, bf16x8& pa0, bf16x8& pa1, bf16x8& pa2, bf16x8& pa3) {
; #pragma unroll
;   for (int r = 0; r < 16; ++r) p1[r] = __builtin_amdgcn_exp2f(p1[r]);
;   float ps = 0;
; #pragma unroll
;   for (int r = 0; r < 16; ++r) ps += p0[r];
; #pragma unroll
;   for (int r = 0; r < 16; ++r) ps += p1[r];
;   { auto rr = __builtin_amdgcn_permlane32_swap(__float_as_uint(ps), __float_as_uint(ps), false, false);
;     ps = __uint_as_float(rr[0]) + __uint_as_float(rr[1]); }
;   l_reg = l_reg * alpha + ps;
;     ...
;   PK4(p0, 0, pa0); PK4(p0, 8, pa1); PK4(p1, 0, pa2); PK4(p1, 8, pa3);
; template <int DQK, bool WIN, bool TWO>
; DEV void attn_unit(const bf16_t* Qb, int ldq, const bf16_t* __restrict__ Kh, int ldk, const bf16_t* __restrict__ Vh, int ldv,
;                    bf16_t* Ob, int ldo, int kbeg, int NT, int q0, float sink, const float SCALE, char* lds) {
;     ...
;     if (j + 1 < NT) { SWAIT(); if (bf) SWRITE(0); else SWRITE(1); }
.Lmla_exp:
	v_mov_b32_e32 v189, v79
	v_exp_f32_e32 v79, v80
	v_exp_f32_e32 v190, v81
	v_exp_f32_e32 v82, v82
	v_exp_f32_e32 v83, v83
	v_exp_f32_e32 v84, v84
	v_exp_f32_e32 v191, v68
	v_add_f32_e32 v68, 0, v79
	v_exp_f32_e32 v85, v85
	v_add_f32_e32 v68, v190, v68
	v_exp_f32_e32 v86, v86
	v_add_f32_e32 v68, v82, v68
	v_exp_f32_e32 v87, v87
	v_add_f32_e32 v68, v83, v68
	v_exp_f32_e32 v88, v88
	v_add_f32_e32 v68, v84, v68
	v_exp_f32_e32 v89, v89
	s_bitcmp0_b32 s100, 0
	s_cbranch_scc0 .Lmla_lw_skip
	s_bitcmp1_b32 s100, 2
	s_cbranch_scc1 .Lmla_lw_skip
	s_waitcnt vmcnt(0)
	s_add_i32 s3, s101, 1
	s_cmp_eq_u32 s3, 3
	s_cselect_b32 s3, 0, s3
	s_lshl_b32 s2, s3, 14
	s_cmp_eq_u32 s3, 2
	s_cselect_b32 s3, 0x15000, s2
	s_xor_b32 s2, s18, 1
	s_mul_i32 s2, s2, 0x6400
	v_add_u32_e32 v198, s3, v179
	v_add_u32_e32 v199, s3, v180
	v_add_u32_e32 v200, s2, v182
	v_add_u32_e32 v201, s2, v183
	v_add_u32_e32 v202, s2, v184
	ds_write_b128 v198, v[144:147]
	ds_write_b128 v199, v[148:151]
	ds_write_b128 v200, v[152:155] offset:32768
	ds_write_b128 v201, v[156:159] offset:32768
	ds_write_b128 v202, v[160:163] offset:32768
.Lmla_lw_skip:
	v_add_f32_e32 v68, v85, v68
	v_exp_f32_e32 v90, v90
	v_add_f32_e32 v68, v86, v68
	v_exp_f32_e32 v91, v91
	v_add_f32_e32 v68, v87, v68
	v_exp_f32_e32 v92, v92
	v_add_f32_e32 v68, v88, v68
	v_exp_f32_e32 v93, v93
	v_add_f32_e32 v68, v89, v68
	v_exp_f32_e32 v94, v94
	v_add_f32_e32 v68, v90, v68
	v_exp_f32_e32 v95, v95
	v_add_f32_e32 v68, v91, v68
	v_exp_f32_e32 v64, v64
	v_add_f32_e32 v68, v92, v68
	v_exp_f32_e32 v65, v65
	v_add_f32_e32 v68, v93, v68
	v_exp_f32_e32 v66, v66
	v_add_f32_e32 v68, v94, v68
	v_exp_f32_e32 v67, v67
	v_add_f32_e32 v68, v95, v68
	v_add_f32_e32 v68, v64, v68
	v_exp_f32_e32 v198, v69
	v_add_f32_e32 v68, v65, v68
	v_exp_f32_e32 v199, v70
	v_add_f32_e32 v68, v66, v68
	v_exp_f32_e32 v200, v71
	v_add_f32_e32 v68, v67, v68
	v_exp_f32_e32 v201, v72
	v_add_f32_e32 v68, v191, v68
	v_exp_f32_e32 v202, v73
	v_add_f32_e32 v68, v198, v68
	v_exp_f32_e32 v203, v74
	v_add_f32_e32 v68, v199, v68
	v_exp_f32_e32 v213, v75
	v_add_f32_e32 v68, v200, v68
	v_exp_f32_e32 v214, v76
	v_add_f32_e32 v68, v201, v68
	v_exp_f32_e32 v215, v77
	v_add_f32_e32 v68, v202, v68
	v_exp_f32_e32 v216, v78
	v_add_f32_e32 v68, v203, v68
	v_exp_f32_e32 v189, v189
	v_add_f32_e32 v68, v213, v68
	v_add_f32_e32 v68, v214, v68
	v_add_f32_e32 v68, v215, v68
	v_add_f32_e32 v68, v216, v68
	v_add_f32_e32 v80, v189, v68
	v_mov_b32_e32 v81, v80
	v_cvt_pk_bf16_f32 v68, v79, v190
	v_cvt_pk_bf16_f32 v69, v82, v83
	v_cvt_pk_bf16_f32 v70, v84, v85
	v_cvt_pk_bf16_f32 v71, v86, v87
	v_cvt_pk_bf16_f32 v72, v88, v89
	v_cvt_pk_bf16_f32 v73, v90, v91
	v_cvt_pk_bf16_f32 v74, v92, v93
	v_cvt_pk_bf16_f32 v75, v94, v95
	v_cvt_pk_bf16_f32 v76, v64, v65
	v_cvt_pk_bf16_f32 v77, v66, v67
	v_cvt_pk_bf16_f32 v78, v191, v198
	v_cvt_pk_bf16_f32 v79, v199, v200
	v_cvt_pk_bf16_f32 v64, v201, v202
	v_cvt_pk_bf16_f32 v65, v203, v213
	v_cvt_pk_bf16_f32 v66, v214, v215
	v_cvt_pk_bf16_f32 v67, v216, v189
	v_permlane32_swap_b32_e32 v80, v81
	v_permlane32_swap_b32_e32 v68, v70
	v_permlane32_swap_b32_e32 v69, v71
	v_permlane32_swap_b32_e32 v72, v74
	v_permlane32_swap_b32_e32 v73, v75
	v_permlane32_swap_b32_e32 v76, v78
	v_permlane32_swap_b32_e32 v77, v79
	v_permlane32_swap_b32_e32 v64, v66
	v_permlane32_swap_b32_e32 v65, v67
	v_add_f32_e32 v144, v80, v81
	v_cmp_ge_f32_e32 vcc, 0x47800000, v144
	s_cmp_eq_u64 vcc, exec
	s_cbranch_scc1 .Lmla_ok
	s_bitcmp1_b32 s100, 2
	s_cbranch_scc0 .Lmla_redo
